# v132 + S5 pass B software pipelining (next tile projection inside recurrence) + attention no-mask e-formulation
# speedup vs baseline: 1.0026x; 1.0004x over previous
; #define LAS __attribute__((address_space(3)))
; #define LDS_WAIT() asm volatile("s_waitcnt lgkmcnt(0)" ::: "memory")
; template <bool PASSB>
; __device__ __forceinline__ void s5_phase(LAS unsigned char* lds, const Params& p) {
;     ...
;         const size_t row0 = (size_t)b * SEQ + (size_t)c * S5_LC;
;         const bf16_t* up = U + ((size_t)g * T + row0 + fr) * 16 + (fq & 1) * 8;
;         bf16x8 au_q0 = (fq < 2) ? *(const bf16x8*)up : zero8;
;         bf16x8 au_q1 = (fq < 2) ? *(const bf16x8*)(up + (size_t)1 * 16 * 16) : zero8;
;         bf16x8 au_q2 = (fq < 2) ? *(const bf16x8*)(up + (size_t)2 * 16 * 16) : zero8;
;         constexpr int NST = S5_LC / 16;
;         for (int st = 0; st < NST; ++st) {
;             const size_t r0 = row0 + st * 16;
;             const bf16x8 au = au_q0; au_q0 = au_q1; au_q1 = au_q2;
;             if (st + 3 < NST) au_q2 = (fq < 2) ? *(const bf16x8*)(up + (size_t)(st + 3) * 16 * 16) : zero8;
; #pragma unroll
;             for (int nb = 0; nb < 8; ++nb) {
;                 const f32x4 d = __builtin_amdgcn_mfma_f32_16x16x32_bf16(au, bfm[nb], (f32x4){0.f, 0.f, 0.f, 0.f}, 0, 0, 0);
;                 *(LAS f32x4*)(BuL + (nb * 16 + fr) * 20 + fq * 4) = d;
;             }
;             LDS_WAIT();
;             f32x4 br4[4], bi4[4];
; #pragma unroll
;             for (int q = 0; q < 4; ++q) { br4[q] = *(const LAS f32x4*)(BuL + lane * 20 + q * 4); bi4[q] = *(const LAS f32x4*)(BuL + (64 + lane) * 20 + q * 4); }
.LBB0_1092:
	s_or_b64 exec, exec, s[24:25]
	v_and_b32_e32 v1, 63, v105
	v_lshl_or_b32 v98, v1, 15, v72
	v_mov_b32_e32 v99, v73
	v_lshl_add_u64 v[64:65], v[98:99], 0, v[64:65]
	v_lshl_add_u64 v[64:65], v[64:65], 0, v[66:67]
	v_lshlrev_b32_e32 v2, 5, v93
	v_mov_b32_e32 v3, v0
	v_lshlrev_b64 v[64:65], 5, v[64:65]
	v_lshl_add_u64 v[2:3], v[82:83], 0, v[2:3]
	v_mov_b32_e32 v89, v88
	v_mov_b32_e32 v93, v92
	v_lshl_add_u64 v[98:99], v[84:85], 0, v[64:65]
	s_mov_b32 s23, 0
	v_mov_b64_e32 v[100:101], v[86:87]
	v_or_b32_e32 v145, v97, v101
	v_or_b32_e32 v144, v96, v100
	v_lshlrev_b64 v[144:145], 11, v[144:145]
	s_mov_b64 s[80:81], 0x1000
	v_lshl_add_u64 v[144:145], v[2:3], 0, v[144:145]
	v_lshl_add_u64 v[146:147], v[144:145], 0, s[80:81]
	s_mov_b64 s[82:83], 0x8000
	v_add_u32_e32 v158, 0x2800, v109
	v_add_u32_e32 v159, 0x2c40, v109
	v_add_u32_e32 v160, 0x3080, v109
	v_add_u32_e32 v161, 0x34c0, v109
	s_waitcnt vmcnt(0)
	v_mfma_f32_16x16x32_bf16 v[172:175], v[68:71], v[8:11], 0
	v_mfma_f32_16x16x32_bf16 v[176:179], v[68:71], v[4:7], 0
	v_mfma_f32_16x16x32_bf16 v[180:183], v[68:71], v[16:19], 0
	v_mfma_f32_16x16x32_bf16 v[184:187], v[68:71], v[12:15], 0
	v_mfma_f32_16x16x32_bf16 v[188:191], v[68:71], v[20:23], 0
	s_nop 7
	ds_write_b128 v107, v[172:175]
	ds_write_b128 v107, v[176:179] offset:1280
	ds_write_b128 v107, v[180:183] offset:2560
	ds_write_b128 v107, v[184:187] offset:3840
	s_nop 1
	ds_write_b128 v107, v[188:191] offset:5120
	v_mfma_f32_16x16x32_bf16 v[172:175], v[68:71], v[24:27], 0
	v_mfma_f32_16x16x32_bf16 v[176:179], v[68:71], v[28:31], 0
	v_mfma_f32_16x16x32_bf16 v[180:183], v[68:71], v[32:35], 0
	s_nop 7
	s_nop 1
	ds_write_b128 v107, v[172:175] offset:6400
	ds_write_b128 v107, v[176:179] offset:7680
	ds_write_b128 v107, v[180:183] offset:8960
	s_waitcnt lgkmcnt(0)
	ds_read_b128 v[112:115], v108
	ds_read_b128 v[116:119], v108 offset:16
	ds_read_b128 v[120:123], v108 offset:32
	ds_read_b128 v[124:127], v108 offset:48
	ds_read_b128 v[128:131], v108 offset:5120
	ds_read_b128 v[132:135], v108 offset:5136
	ds_read_b128 v[136:139], v108 offset:5152
	ds_read_b128 v[140:143], v108 offset:5168
	s_branch .LBB0_1094
; #define LAS __attribute__((address_space(3)))
; __device__ __forceinline__ unsigned cvt_pk_bf16(float lo, float hi) { unsigned r; asm volatile("v_cvt_pk_bf16_f32 %0, %1, %2" : "=v"(r) : "v"(lo), "v"(hi)); return r; }
; template <bool PASSB>
; __device__ __forceinline__ void s5_phase(LAS unsigned char* lds, const Params& p) {
;     ...
;         for (int st = 0; st < NST; ++st) {
;             const size_t r0 = row0 + st * 16;
;             const bf16x8 au = au_q0; au_q0 = au_q1; au_q1 = au_q2;
;             if (st + 3 < NST) au_q2 = (fq < 2) ? *(const bf16x8*)(up + (size_t)(st + 3) * 16 * 16) : zero8;
; #pragma unroll
;             for (int nb = 0; nb < 8; ++nb) {
;                 const f32x4 d = __builtin_amdgcn_mfma_f32_16x16x32_bf16(au, bfm[nb], (f32x4){0.f, 0.f, 0.f, 0.f}, 0, 0, 0);
;                 *(LAS f32x4*)(BuL + (nb * 16 + fr) * 20 + fq * 4) = d;
;             }
;             LDS_WAIT();
;             f32x4 br4[4], bi4[4];
; #pragma unroll
;             for (int q = 0; q < 4; ++q) { br4[q] = *(const LAS f32x4*)(BuL + lane * 20 + q * 4); bi4[q] = *(const LAS f32x4*)(BuL + (64 + lane) * 20 + q * 4); }
; #pragma unroll
;             for (int t = 0; t < 16; ++t) {
;                 const float bur = br4[t >> 2][t & 3], bui = bi4[t >> 2][t & 3];
;                 const float nr = are * hr - aim * hi + bur, ni = are * hi + aim * hr + bui; hr = nr; hi = ni;
;                 if (PASSB) *(LAS unsigned*)(HbL + t * 272 + lane * 4) = cvt_pk_bf16(hr, hi);
;             }
;             if (PASSB) {
;                 LDS_WAIT();
;                 f32x4 y = __builtin_amdgcn_mfma_f32_16x16x32_bf16(au, dfm, (f32x4){0.f, 0.f, 0.f, 0.f}, 0, 0, 0);
; #pragma unroll
;                 for (int ks = 0; ks < 4; ++ks) {
;                     const bf16x8 a = *(const LAS bf16x8*)(HbL + fr * 272 + (ks * 32 + fq * 8) * 2);
;                     y = __builtin_amdgcn_mfma_f32_16x16x32_bf16(a, cfm[ks], y, 0, 0, 0);
;                 }
; #pragma unroll
;                 for (int j = 0; j < 4; ++j) {
;                     const float v = y[j];
;                     const float ge = v * sigmoidf_(1.5957691216057308f * (v + 0.044715f * v * v * v));
;                     YG[(r0 + fq * 4 + j) * 1024 + g * 16 + fr] = (bf16_t)(cvt_pk_bf16(ge, ge) & 0xffffu);
;                 }
;             }
;             LDS_WAIT();
;         }
.LBB0_1093:
	s_or_b64 exec, exec, s[24:25]
	s_add_i32 s23, s23, 1
	v_lshl_add_u64 v[98:99], v[98:99], 0, s[64:65]
	s_cmp_eq_u32 s23, 32
	v_mfma_f32_16x16x32_bf16 v[68:71], v[68:71], v[52:55], 0
	s_waitcnt lgkmcnt(0)
	v_fmac_f32_e32 v112, v88, v94
	v_fmac_f32_e32 v128, v88, v95
	v_fma_f32 v112, -v92, v95, v112
	v_fmac_f32_e32 v128, v92, v94
	v_cvt_pk_bf16_f32 v1, v112, v128
	v_fmac_f32_e32 v113, v88, v112
	v_fmac_f32_e32 v129, v88, v128
	v_fma_f32 v113, -v92, v128, v113
	v_fmac_f32_e32 v129, v92, v112
	v_cvt_pk_bf16_f32 v152, v113, v129
	ds_write2_b32 v158, v1, v152 offset0:0 offset1:68
	v_mfma_f32_16x16x32_bf16 v[172:175], v[64:67], v[8:11], 0
	v_mfma_f32_16x16x32_bf16 v[176:179], v[64:67], v[4:7], 0
	v_fmac_f32_e32 v114, v88, v113
	v_fmac_f32_e32 v130, v88, v129
	v_fma_f32 v114, -v92, v129, v114
	v_fmac_f32_e32 v130, v92, v113
	v_cvt_pk_bf16_f32 v1, v114, v130
	v_fmac_f32_e32 v115, v88, v114
	v_fmac_f32_e32 v131, v88, v130
	v_fma_f32 v115, -v92, v130, v115
	v_fmac_f32_e32 v131, v92, v114
	v_cvt_pk_bf16_f32 v152, v115, v131
	ds_write2_b32 v158, v1, v152 offset0:136 offset1:204
	ds_write_b128 v107, v[172:175]
	v_mfma_f32_16x16x32_bf16 v[180:183], v[64:67], v[16:19], 0
	v_mfma_f32_16x16x32_bf16 v[184:187], v[64:67], v[12:15], 0
	ds_write_b128 v107, v[176:179] offset:1280
	v_fmac_f32_e32 v116, v88, v115
	v_fmac_f32_e32 v132, v88, v131
	v_fma_f32 v116, -v92, v131, v116
	v_fmac_f32_e32 v132, v92, v115
	v_cvt_pk_bf16_f32 v1, v116, v132
	v_fmac_f32_e32 v117, v88, v116
	v_fmac_f32_e32 v133, v88, v132
	v_fma_f32 v117, -v92, v132, v117
	v_fmac_f32_e32 v133, v92, v116
	v_cvt_pk_bf16_f32 v152, v117, v133
	ds_write2_b32 v159, v1, v152 offset0:0 offset1:68
	ds_write_b128 v107, v[180:183] offset:2560
	ds_write_b128 v107, v[184:187] offset:3840
	v_mfma_f32_16x16x32_bf16 v[188:191], v[64:67], v[20:23], 0
	v_mfma_f32_16x16x32_bf16 v[172:175], v[64:67], v[24:27], 0
	v_mfma_f32_16x16x32_bf16 v[176:179], v[64:67], v[28:31], 0
	v_fmac_f32_e32 v118, v88, v117
	v_fmac_f32_e32 v134, v88, v133
	v_fma_f32 v118, -v92, v133, v118
	v_fmac_f32_e32 v134, v92, v117
	v_cvt_pk_bf16_f32 v1, v118, v134
	v_fmac_f32_e32 v119, v88, v118
	v_fmac_f32_e32 v135, v88, v134
	v_fma_f32 v119, -v92, v134, v119
	v_fmac_f32_e32 v135, v92, v118
	v_cvt_pk_bf16_f32 v152, v119, v135
	ds_write2_b32 v159, v1, v152 offset0:136 offset1:204
	ds_write_b128 v107, v[188:191] offset:5120
	ds_write_b128 v107, v[172:175] offset:6400
	ds_write_b128 v107, v[176:179] offset:7680
	v_mfma_f32_16x16x32_bf16 v[172:175], v[64:67], v[32:35], 0
	v_fmac_f32_e32 v120, v88, v119
	v_fmac_f32_e32 v136, v88, v135
	v_fma_f32 v120, -v92, v135, v120
	v_fmac_f32_e32 v136, v92, v119
	v_cvt_pk_bf16_f32 v1, v120, v136
	v_fmac_f32_e32 v121, v88, v120
	v_fmac_f32_e32 v137, v88, v136
	v_fma_f32 v121, -v92, v136, v121
	v_fmac_f32_e32 v137, v92, v120
	v_cvt_pk_bf16_f32 v152, v121, v137
	ds_write2_b32 v160, v1, v152 offset0:0 offset1:68
	ds_write_b128 v107, v[172:175] offset:8960
	v_fmac_f32_e32 v122, v88, v121
	v_fmac_f32_e32 v138, v88, v137
	v_fma_f32 v122, -v92, v137, v122
	v_fmac_f32_e32 v138, v92, v121
	v_cvt_pk_bf16_f32 v1, v122, v138
	v_fmac_f32_e32 v123, v88, v122
	v_fmac_f32_e32 v139, v88, v138
	v_fma_f32 v123, -v92, v138, v123
	v_fmac_f32_e32 v139, v92, v122
	v_cvt_pk_bf16_f32 v152, v123, v139
	ds_write2_b32 v160, v1, v152 offset0:136 offset1:204
	v_fmac_f32_e32 v124, v88, v123
	v_fmac_f32_e32 v140, v88, v139
	v_fma_f32 v124, -v92, v139, v124
	v_fmac_f32_e32 v140, v92, v123
	v_cvt_pk_bf16_f32 v1, v124, v140
	v_fmac_f32_e32 v125, v88, v124
	v_fmac_f32_e32 v141, v88, v140
	v_fma_f32 v125, -v92, v140, v125
	v_fmac_f32_e32 v141, v92, v124
	v_cvt_pk_bf16_f32 v152, v125, v141
	ds_write2_b32 v161, v1, v152 offset0:0 offset1:68
	v_fmac_f32_e32 v126, v88, v125
	v_fmac_f32_e32 v142, v88, v141
	v_fma_f32 v126, -v92, v141, v126
	v_fmac_f32_e32 v142, v92, v125
	v_cvt_pk_bf16_f32 v1, v126, v142
	v_fmac_f32_e32 v127, v88, v126
	v_fmac_f32_e32 v143, v88, v142
	v_fma_f32 v127, -v92, v142, v127
	v_fmac_f32_e32 v143, v92, v126
	v_cvt_pk_bf16_f32 v152, v127, v143
	ds_write2_b32 v161, v1, v152 offset0:136 offset1:204
	v_mov_b32_e32 v94, v127
	v_mov_b32_e32 v95, v143
	s_waitcnt lgkmcnt(0)
	ds_read_b128 v[112:115], v110 offset:10240
	ds_read_b128 v[116:119], v110 offset:10304
	s_waitcnt lgkmcnt(1)
	v_mfma_f32_16x16x32_bf16 v[68:71], v[112:115], v[36:39], v[68:71]
	ds_read_b128 v[112:115], v110 offset:10368
	s_waitcnt lgkmcnt(1)
	v_mfma_f32_16x16x32_bf16 v[68:71], v[116:119], v[40:43], v[68:71]
	ds_read_b128 v[116:119], v110 offset:10432
	s_waitcnt lgkmcnt(1)
	v_mfma_f32_16x16x32_bf16 v[68:71], v[112:115], v[44:47], v[68:71]
	s_waitcnt lgkmcnt(0)
	v_mfma_f32_16x16x32_bf16 v[68:71], v[116:119], v[48:51], v[68:71]
	ds_read_b128 v[112:115], v108
	ds_read_b128 v[116:119], v108 offset:16
	ds_read_b128 v[120:123], v108 offset:32
	ds_read_b128 v[124:127], v108 offset:48
	ds_read_b128 v[128:131], v108 offset:5120
	ds_read_b128 v[132:135], v108 offset:5136
	ds_read_b128 v[136:139], v108 offset:5152
	ds_read_b128 v[140:143], v108 offset:5168
	s_nop 0
	v_mul_f32_e32 v148, 0x3d372713, v68
	v_mul_f32_e32 v149, 0x3d372713, v69
	v_mul_f32_e32 v150, 0x3d372713, v70
	v_mul_f32_e32 v151, 0x3d372713, v71
	v_mul_f32_e32 v148, v68, v148
	v_mul_f32_e32 v149, v69, v149
	v_mul_f32_e32 v150, v70, v150
	v_mul_f32_e32 v151, v71, v151
	v_fma_f32 v148, v68, v148, v68
	v_fma_f32 v149, v69, v149, v69
	v_fma_f32 v150, v70, v150, v70
	v_fma_f32 v151, v71, v151, v71
	v_mul_f32_e32 v148, 0xc0135761, v148
	v_mul_f32_e32 v149, 0xc0135761, v149
	v_mul_f32_e32 v150, 0xc0135761, v150
	v_mul_f32_e32 v151, 0xc0135761, v151
	v_exp_f32_e32 v148, v148
	v_exp_f32_e32 v149, v149
	v_exp_f32_e32 v150, v150
	v_exp_f32_e32 v151, v151
	v_add_f32_e32 v148, 1.0, v148
	v_add_f32_e32 v149, 1.0, v149
	v_add_f32_e32 v150, 1.0, v150
	v_add_f32_e32 v151, 1.0, v151
	v_rcp_f32_e32 v148, v148
	v_rcp_f32_e32 v149, v149
	v_rcp_f32_e32 v150, v150
	v_rcp_f32_e32 v151, v151
	v_mul_f32_e32 v148, v68, v148
	v_mul_f32_e32 v149, v69, v149
	v_mul_f32_e32 v150, v70, v150
	v_mul_f32_e32 v151, v71, v151
	v_cvt_pk_bf16_f32 v148, v148, v149
	v_cvt_pk_bf16_f32 v150, v150, v151
	global_store_short v[144:145], v148, off
	global_store_short_d16_hi v[144:145], v148, off offset:2048
	global_store_short v[146:147], v150, off
	global_store_short_d16_hi v[146:147], v150, off offset:2048
	v_lshl_add_u64 v[144:145], v[144:145], 0, s[82:83]
	v_lshl_add_u64 v[146:147], v[146:147], 0, s[82:83]
	s_waitcnt lgkmcnt(0)
	v_mov_b64_e32 v[70:71], v[66:67]
	v_mov_b64_e32 v[68:69], v[64:65]
	s_cbranch_scc1 .LBB0_1061
